# GEMM tile loops: 128 accumulator-zeroing v_mov_b32 per tile replaced by 64 v_mov_b64
# speedup vs baseline: 1.0009x; 1.0009x over previous
; template <bool GATHER, bool FP8, class Epi, class Sched>
; __device__ __forceinline__ void gemm_phase(LAS unsigned char* lds, const int tid, const int K, const Sched& S, const Epi& E) {
;     ...
; #pragma unroll
;         for (int a = 0; a < 2; ++a)
; #pragma unroll
;             for (int b = 0; b < 2; ++b)
; #pragma unroll
;                 for (int m = 0; m < 4; ++m)
; #pragma unroll
;                     for (int n = 0; n < 2; ++n) acc[a][b][m][n] = (f32x4){zf, zf, zf, zf};
;         cur = nxt; cA = nA; cB = nB; ++ui;
.LBB0_41:
	s_ashr_i32 s51, s50, 31
	s_lshl_b64 s[26:27], s[50:51], 18
	v_readlane_b32 s0, v251, 21
	v_readlane_b32 s1, v251, 22
	s_add_u32 s52, s0, s26
	s_addc_u32 s53, s1, s27
	s_and_b64 s[26:27], s[44:45], exec
	s_cselect_b32 s12, s53, s21
	s_cselect_b32 s17, s52, s20
	s_ashr_i32 s47, s46, 31
	s_lshl_b64 s[26:27], s[46:47], 20
	v_readlane_b32 s0, v254, 51
	s_add_u32 s0, s0, s26
	v_readlane_b32 s1, v254, 52
	s_addc_u32 s1, s1, s27
	s_ashr_i32 s39, s38, 31
	s_lshl_b64 s[26:27], s[38:39], 18
	s_add_u32 s54, s0, s26
	s_addc_u32 s55, s1, s27
	s_and_b64 s[26:27], s[44:45], exec
	s_cselect_b32 s39, s55, s23
	s_cselect_b32 s47, s54, s22
	s_add_u32 s51, s22, 0x10000
	s_addc_u32 s57, s23, 0
	s_add_u32 s20, s20, 0x20080
	s_addc_u32 s21, s21, 0
	s_mov_b32 vcc_lo, -2
	v_mov_b64_e32 v[34:35], 0
	v_mov_b64_e32 v[36:37], 0
	v_mov_b64_e32 v[40:41], 0
	v_mov_b64_e32 v[42:43], 0
	v_mov_b64_e32 v[52:53], 0
	v_mov_b64_e32 v[54:55], 0
	v_mov_b64_e32 v[56:57], 0
	v_mov_b64_e32 v[58:59], 0
	v_mov_b64_e32 v[68:69], 0
	v_mov_b64_e32 v[70:71], 0
	v_mov_b64_e32 v[72:73], 0
	v_mov_b64_e32 v[74:75], 0
	v_mov_b64_e32 v[84:85], 0
	v_mov_b64_e32 v[86:87], 0
	v_mov_b64_e32 v[88:89], 0
	v_mov_b64_e32 v[90:91], 0
	v_mov_b64_e32 v[44:45], 0
	v_mov_b64_e32 v[46:47], 0
	v_mov_b64_e32 v[48:49], 0
	v_mov_b64_e32 v[50:51], 0
	v_mov_b64_e32 v[60:61], 0
	v_mov_b64_e32 v[62:63], 0
	v_mov_b64_e32 v[64:65], 0
	v_mov_b64_e32 v[66:67], 0
	v_mov_b64_e32 v[76:77], 0
	v_mov_b64_e32 v[78:79], 0
	v_mov_b64_e32 v[80:81], 0
	v_mov_b64_e32 v[82:83], 0
	v_mov_b64_e32 v[92:93], 0
	v_mov_b64_e32 v[94:95], 0
	v_mov_b64_e32 v[96:97], 0
	v_mov_b64_e32 v[98:99], 0
	v_mov_b64_e32 v[100:101], 0
	v_mov_b64_e32 v[102:103], 0
	v_mov_b64_e32 v[104:105], 0
	v_mov_b64_e32 v[106:107], 0
	v_mov_b64_e32 v[116:117], 0
	v_mov_b64_e32 v[118:119], 0
	v_mov_b64_e32 v[120:121], 0
	v_mov_b64_e32 v[122:123], 0
	v_mov_b64_e32 v[132:133], 0
	v_mov_b64_e32 v[134:135], 0
	v_mov_b64_e32 v[136:137], 0
	v_mov_b64_e32 v[138:139], 0
	v_mov_b64_e32 v[148:149], 0
	v_mov_b64_e32 v[150:151], 0
	v_mov_b64_e32 v[152:153], 0
	v_mov_b64_e32 v[154:155], 0
	v_mov_b64_e32 v[108:109], 0
	v_mov_b64_e32 v[110:111], 0
	v_mov_b64_e32 v[112:113], 0
	v_mov_b64_e32 v[114:115], 0
	v_mov_b64_e32 v[124:125], 0
	v_mov_b64_e32 v[126:127], 0
	v_mov_b64_e32 v[128:129], 0
	v_mov_b64_e32 v[130:131], 0
	v_mov_b64_e32 v[140:141], 0
	v_mov_b64_e32 v[142:143], 0
	v_mov_b64_e32 v[144:145], 0
	v_mov_b64_e32 v[146:147], 0
	v_mov_b64_e32 v[156:157], 0
	v_mov_b64_e32 v[158:159], 0
	v_mov_b64_e32 v[160:161], 0
	v_mov_b64_e32 v[162:163], 0

; template <bool GATHER, bool FP8, class Epi, class Sched>
; __device__ __forceinline__ void gemm_phase(LAS unsigned char* lds, const int tid, const int K, const Sched& S, const Epi& E) {
;     ...
; #pragma unroll
;         for (int a = 0; a < 2; ++a)
; #pragma unroll
;             for (int b = 0; b < 2; ++b)
; #pragma unroll
;                 for (int m = 0; m < 4; ++m)
; #pragma unroll
;                     for (int n = 0; n < 2; ++n) acc[a][b][m][n] = (f32x4){zf, zf, zf, zf};
;         cur = nxt; cA = nA; cB = nB; ++ui;
.LBB0_93:
	s_ashr_i32 s51, s50, 31
	s_lshl_b64 s[16:17], s[50:51], 21
	v_readlane_b32 s12, v254, 55
	s_add_u32 s12, s12, s16
	v_readlane_b32 s16, v254, 56
	s_addc_u32 s20, s16, s17
	s_ashr_i32 s41, s40, 31
	s_lshl_b64 s[16:17], s[40:41], 18
	s_add_u32 s52, s12, s16
	s_addc_u32 s53, s20, s17
	s_and_b64 s[16:17], s[44:45], exec
	s_cselect_b32 s41, s53, s23
	s_cselect_b32 s51, s52, s22
	s_lshl_b32 s16, s73, 9
	s_add_u32 s17, s22, 0x10000
	v_readlane_b32 s20, v251, 39
	v_mov_b32_e32 v178, v188
	v_mov_b32_e32 v179, v33
	v_mov_b32_e32 v180, v190
	v_mov_b32_e32 v181, v33
	s_addc_u32 s12, s23, 0
	s_mov_b32 s71, -2
	v_readlane_b32 s21, v251, 40
	v_mov_b64_e32 v[34:35], 0
	v_mov_b64_e32 v[36:37], 0
	v_mov_b64_e32 v[40:41], 0
	v_mov_b64_e32 v[42:43], 0
	v_mov_b64_e32 v[52:53], 0
	v_mov_b64_e32 v[54:55], 0
	v_mov_b64_e32 v[56:57], 0
	v_mov_b64_e32 v[58:59], 0
	v_mov_b64_e32 v[68:69], 0
	v_mov_b64_e32 v[70:71], 0
	v_mov_b64_e32 v[72:73], 0
	v_mov_b64_e32 v[74:75], 0
	v_mov_b64_e32 v[84:85], 0
	v_mov_b64_e32 v[86:87], 0
	v_mov_b64_e32 v[88:89], 0
	v_mov_b64_e32 v[90:91], 0
	v_mov_b64_e32 v[44:45], 0
	v_mov_b64_e32 v[46:47], 0
	v_mov_b64_e32 v[48:49], 0
	v_mov_b64_e32 v[50:51], 0
	v_mov_b64_e32 v[60:61], 0
	v_mov_b64_e32 v[62:63], 0
	v_mov_b64_e32 v[64:65], 0
	v_mov_b64_e32 v[66:67], 0
	v_mov_b64_e32 v[76:77], 0
	v_mov_b64_e32 v[78:79], 0
	v_mov_b64_e32 v[80:81], 0
	v_mov_b64_e32 v[82:83], 0
	v_mov_b64_e32 v[92:93], 0
	v_mov_b64_e32 v[94:95], 0
	v_mov_b64_e32 v[96:97], 0
	v_mov_b64_e32 v[98:99], 0
	v_mov_b64_e32 v[100:101], 0
	v_mov_b64_e32 v[102:103], 0
	v_mov_b64_e32 v[104:105], 0
	v_mov_b64_e32 v[106:107], 0
	v_mov_b64_e32 v[116:117], 0
	v_mov_b64_e32 v[118:119], 0
	v_mov_b64_e32 v[120:121], 0
	v_mov_b64_e32 v[122:123], 0
	v_mov_b64_e32 v[132:133], 0
	v_mov_b64_e32 v[134:135], 0
	v_mov_b64_e32 v[136:137], 0
	v_mov_b64_e32 v[138:139], 0
	v_mov_b64_e32 v[148:149], 0
	v_mov_b64_e32 v[150:151], 0
	v_mov_b64_e32 v[152:153], 0
	v_mov_b64_e32 v[154:155], 0
	v_mov_b64_e32 v[108:109], 0
	v_mov_b64_e32 v[110:111], 0
	v_mov_b64_e32 v[112:113], 0
	v_mov_b64_e32 v[114:115], 0
	v_mov_b64_e32 v[124:125], 0
	v_mov_b64_e32 v[126:127], 0
	v_mov_b64_e32 v[128:129], 0
	v_mov_b64_e32 v[130:131], 0
	v_mov_b64_e32 v[140:141], 0
	v_mov_b64_e32 v[142:143], 0
	v_mov_b64_e32 v[144:145], 0
	v_mov_b64_e32 v[146:147], 0
	v_mov_b64_e32 v[156:157], 0
	v_mov_b64_e32 v[158:159], 0
	v_mov_b64_e32 v[160:161], 0
	v_mov_b64_e32 v[162:163], 0
	s_branch .LBB0_95

; template <bool GATHER, bool FP8, class Epi, class Sched>
; __device__ __forceinline__ void gemm_phase(LAS unsigned char* lds, const int tid, const int K, const Sched& S, const Epi& E) {
;     ...
; #pragma unroll
;         for (int a = 0; a < 2; ++a)
; #pragma unroll
;             for (int b = 0; b < 2; ++b)
; #pragma unroll
;                 for (int m = 0; m < 4; ++m)
; #pragma unroll
;                     for (int n = 0; n < 2; ++n) acc[a][b][m][n] = (f32x4){zf, zf, zf, zf};
;         cur = nxt; cA = nA; cB = nB; ++ui;
.LBB0_161:
	s_ashr_i32 s41, s40, 31
	s_lshl_b64 s[26:27], s[40:41], 19
	s_add_u32 s44, s68, s26
	s_addc_u32 s45, s69, s27
	s_and_b64 s[26:27], s[36:37], exec
	s_cselect_b32 s41, s45, s21
	s_cselect_b32 s61, s44, s20
	s_ashr_i32 s39, s38, 31
	s_lshl_b64 s[26:27], s[38:39], 19
	v_readlane_b32 s39, v249, 38
	s_add_u32 s46, s39, s26
	v_readlane_b32 s26, v249, 39
	s_addc_u32 s47, s26, s27
	s_and_b64 s[26:27], s[36:37], exec
	s_cselect_b32 s39, s47, s23
	s_cselect_b32 s62, s46, s22
	s_add_u32 s63, s22, 0x10000
	s_addc_u32 s64, s23, 0
	s_add_u32 s20, s20, 0x40080
	s_addc_u32 s21, s21, 0
	s_mov_b32 s65, -2
	v_mov_b64_e32 v[0:1], 0
	v_mov_b64_e32 v[2:3], 0
	v_mov_b64_e32 v[4:5], 0
	v_mov_b64_e32 v[6:7], 0
	v_mov_b64_e32 v[16:17], 0
	v_mov_b64_e32 v[18:19], 0
	v_mov_b64_e32 v[20:21], 0
	v_mov_b64_e32 v[22:23], 0
	v_mov_b64_e32 v[34:35], 0
	v_mov_b64_e32 v[36:37], 0
	v_mov_b64_e32 v[40:41], 0
	v_mov_b64_e32 v[42:43], 0
	v_mov_b64_e32 v[48:49], 0
	v_mov_b64_e32 v[50:51], 0
	v_mov_b64_e32 v[56:57], 0
	v_mov_b64_e32 v[58:59], 0
	v_mov_b64_e32 v[8:9], 0
	v_mov_b64_e32 v[10:11], 0
	v_mov_b64_e32 v[12:13], 0
	v_mov_b64_e32 v[14:15], 0
	v_mov_b64_e32 v[24:25], 0
	v_mov_b64_e32 v[26:27], 0
	v_mov_b64_e32 v[28:29], 0
	v_mov_b64_e32 v[30:31], 0
	v_mov_b64_e32 v[44:45], 0
	v_mov_b64_e32 v[46:47], 0
	v_mov_b64_e32 v[52:53], 0
	v_mov_b64_e32 v[54:55], 0
	v_mov_b64_e32 v[68:69], 0
	v_mov_b64_e32 v[70:71], 0
	v_mov_b64_e32 v[72:73], 0
	v_mov_b64_e32 v[74:75], 0
	v_mov_b64_e32 v[84:85], 0
	v_mov_b64_e32 v[86:87], 0
	v_mov_b64_e32 v[88:89], 0
	v_mov_b64_e32 v[90:91], 0
	v_mov_b64_e32 v[96:97], 0
	v_mov_b64_e32 v[98:99], 0
	v_mov_b64_e32 v[104:105], 0
	v_mov_b64_e32 v[106:107], 0
	v_mov_b64_e32 v[116:117], 0
	v_mov_b64_e32 v[118:119], 0
	v_mov_b64_e32 v[120:121], 0
	v_mov_b64_e32 v[122:123], 0
	v_mov_b64_e32 v[128:129], 0
	v_mov_b64_e32 v[130:131], 0
	v_mov_b64_e32 v[136:137], 0
	v_mov_b64_e32 v[138:139], 0
	v_mov_b64_e32 v[92:93], 0
	v_mov_b64_e32 v[94:95], 0
	v_mov_b64_e32 v[100:101], 0
	v_mov_b64_e32 v[102:103], 0
	v_mov_b64_e32 v[108:109], 0
	v_mov_b64_e32 v[110:111], 0
	v_mov_b64_e32 v[112:113], 0
	v_mov_b64_e32 v[114:115], 0
	v_mov_b64_e32 v[124:125], 0
	v_mov_b64_e32 v[126:127], 0
	v_mov_b64_e32 v[132:133], 0
	v_mov_b64_e32 v[134:135], 0
	v_mov_b64_e32 v[140:141], 0
	v_mov_b64_e32 v[142:143], 0
	v_mov_b64_e32 v[144:145], 0
	v_mov_b64_e32 v[146:147], 0

; template <bool GATHER, bool FP8, class Epi, class Sched>
; __device__ __forceinline__ void gemm_phase(LAS unsigned char* lds, const int tid, const int K, const Sched& S, const Epi& E) {
;     ...
;         const bool has_next = S.next(ui + 1, nxt);
;         if constexpr (Epi::LDSBIAS) { if (wid == 0) E.stage_bias(lds + BIAS_OFF + (ui & 1) * 1024, cur); }
;         const char* nA = has_next ? S.aptr(nxt) : cA; const char* nB = has_next ? S.bptr(nxt) : cB;
; #pragma unroll 1
;         for (int t = 0; t < nt; t += 2) {
;             const bool last = (t == nt - 2);
;             if (GATHER && last && has_next) { PG8_LOADOFF(o2, ui + 1); }
;             const char* a1 = cA + (size_t)(t + 1) * kstep;
;             const char* a2 = last ? nA : cA + (size_t)(t + 2) * kstep; const char* b2 = last ? nB : cB + (size_t)(t + 2) * kstepB;
;             const char* a3 = a2 + kstep; const char* b3 = b2 + kstepB;
;             PG8_LDB(B0, 0, 0); PG8_LDB(B1, 0, 1); PG8_SCHED; PG8_LDA(At, 0, 0); PG8_STAGE(PG8_SA(1, 1), a1 + hsA, oC[1]);
;             PG8_WAIT_V(8); PG8_WAIT_L(0); PG8_BAR; PG8_MMA(0, 0, At, B0); PG8_MMA(0, 1, At, B1); PG8_BAR; PG8_SCHED;
;             PG8_LDA(At, 0, 1); PG8_STAGE(PG8_SB(0, 0), b2, voffB); PG8_STAGE(PG8_SB(0, 1), b2 + hstepB, voffB); PG8_STAGE(PG8_SA(0, 0), a2, o2[0]);
;             PG8_WAIT_V(8); PG8_WAIT_L(0); PG8_BAR; PG8_MMA(1, 0, At, B0); PG8_MMA(1, 1, At, B1); PG8_BAR; PG8_SCHED;
;             PG8_LDB(B0, 1, 0); PG8_LDB(B1, 1, 1); PG8_SCHED; PG8_LDA(At, 1, 0); PG8_STAGE(PG8_SA(0, 1), a2 + hsA, o2[1]);
;             PG8_WAIT_V(8); PG8_WAIT_L(0); PG8_BAR; PG8_MMA(0, 0, At, B0); PG8_MMA(0, 1, At, B1); PG8_BAR; PG8_SCHED;
;             PG8_LDA(At, 1, 1); PG8_STAGE(PG8_SB(1, 0), b3, voffB); PG8_STAGE(PG8_SB(1, 1), b3 + hstepB, voffB); PG8_STAGE(PG8_SA(1, 0), a3, o2[0]);
;             PG8_WAIT_V(8); PG8_WAIT_L(0); PG8_BAR; PG8_MMA(1, 0, At, B0); PG8_MMA(1, 1, At, B1); PG8_BAR; PG8_SCHED;
;         }
;         if (wr == 0) PG8_BAR;
;         { int t2 = tid; asm volatile("" : "+v"(t2)); const int l2 = t2 & 63; E(acc, cur, wr, wc, l2 & 15, l2 >> 4, (const LAS float*)(lds + BIAS_OFF + (ui & 1) * 1024)); }
;         if (!has_next) break;
; #pragma unroll
;         for (int a = 0; a < 2; ++a)
; #pragma unroll
;             for (int b = 0; b < 2; ++b)
; #pragma unroll
;                 for (int m = 0; m < 4; ++m)
; #pragma unroll
.LBB0_382:
	s_ashr_i32 s41, s40, 31
	s_lshl_b64 s[26:27], s[40:41], 19
	v_readlane_b32 s44, v252, 10
	v_readlane_b32 s45, v252, 11
	s_add_u32 s44, s44, s26
	s_addc_u32 s45, s45, s27
	s_and_b64 s[26:27], s[36:37], exec
	s_cselect_b32 s41, s45, s21
	s_cselect_b32 s59, s44, s20
	s_ashr_i32 s39, s38, 31
	s_lshl_b64 s[26:27], s[38:39], 19
	v_readlane_b32 s39, v249, 15
	s_add_u32 s46, s39, s26
	v_readlane_b32 s26, v249, 16
	s_addc_u32 s47, s26, s27
	s_and_b64 s[26:27], s[36:37], exec
	s_cselect_b32 s39, s47, s23
	s_cselect_b32 s60, s46, s22
	s_add_u32 s61, s22, 0x10000
	s_addc_u32 s62, s23, 0
	s_add_u32 s20, s20, 0x40080
	s_addc_u32 s21, s21, 0
	s_mov_b32 s63, -2
	v_mov_b64_e32 v[0:1], 0
	v_mov_b64_e32 v[2:3], 0
	v_mov_b64_e32 v[4:5], 0
	v_mov_b64_e32 v[6:7], 0
	s_waitcnt vmcnt(0)
	v_mov_b64_e32 v[12:13], 0
	v_mov_b64_e32 v[14:15], 0
	v_mov_b64_e32 v[20:21], 0
	v_mov_b64_e32 v[22:23], 0
	v_mov_b64_e32 v[28:29], 0
	v_mov_b64_e32 v[30:31], 0
	v_mov_b64_e32 v[40:41], 0
	v_mov_b64_e32 v[42:43], 0
	v_mov_b64_e32 v[48:49], 0
	v_mov_b64_e32 v[50:51], 0
	v_mov_b64_e32 v[56:57], 0
	v_mov_b64_e32 v[58:59], 0
	v_mov_b64_e32 v[8:9], 0
	v_mov_b64_e32 v[10:11], 0
	v_mov_b64_e32 v[16:17], 0
	v_mov_b64_e32 v[18:19], 0
	v_mov_b64_e32 v[24:25], 0
	v_mov_b64_e32 v[26:27], 0
	v_mov_b64_e32 v[34:35], 0
	v_mov_b64_e32 v[36:37], 0
	v_mov_b64_e32 v[44:45], 0
	v_mov_b64_e32 v[46:47], 0
	v_mov_b64_e32 v[52:53], 0
	v_mov_b64_e32 v[54:55], 0
	v_mov_b64_e32 v[60:61], 0
	v_mov_b64_e32 v[62:63], 0
	v_mov_b64_e32 v[64:65], 0
	v_mov_b64_e32 v[66:67], 0
	v_mov_b64_e32 v[68:69], 0
	v_mov_b64_e32 v[70:71], 0
	v_mov_b64_e32 v[72:73], 0
	v_mov_b64_e32 v[74:75], 0
	v_mov_b64_e32 v[84:85], 0
	v_mov_b64_e32 v[86:87], 0
	v_mov_b64_e32 v[88:89], 0
	v_mov_b64_e32 v[90:91], 0
	v_mov_b64_e32 v[100:101], 0
	v_mov_b64_e32 v[102:103], 0
	v_mov_b64_e32 v[104:105], 0
	v_mov_b64_e32 v[106:107], 0
	v_mov_b64_e32 v[132:133], 0
	v_mov_b64_e32 v[134:135], 0
	v_mov_b64_e32 v[136:137], 0
	v_mov_b64_e32 v[138:139], 0
	v_mov_b64_e32 v[76:77], 0
	v_mov_b64_e32 v[78:79], 0
	v_mov_b64_e32 v[80:81], 0
	v_mov_b64_e32 v[82:83], 0
	v_mov_b64_e32 v[92:93], 0
	v_mov_b64_e32 v[94:95], 0
	v_mov_b64_e32 v[96:97], 0
	v_mov_b64_e32 v[98:99], 0
	v_mov_b64_e32 v[112:113], 0
	v_mov_b64_e32 v[114:115], 0
	v_mov_b64_e32 v[116:117], 0
	v_mov_b64_e32 v[118:119], 0
	v_mov_b64_e32 v[140:141], 0
	v_mov_b64_e32 v[142:143], 0
	v_mov_b64_e32 v[144:145], 0
	v_mov_b64_e32 v[146:147], 0
